# phase-4 GEMM epilogue: per-row-group counted vmcnt waits (two residual-load groups stay in flight) instead of draining loads and stores every second group
# baseline (speedup 1.0000x reference)
.LBB0_476:
	ds_read_b128 v[144:147], v167
	ds_read_b128 v[148:151], v167 offset:1024
	ds_read_b128 v[152:155], v167 offset:2048
	ds_read_b128 v[156:159], v167 offset:3072
	s_add_u32 s60, s58, 0xfff80080
	s_addc_u32 s61, s59, -1
	s_cmp_eq_u32 s84, 28
	s_cselect_b32 s63, s51, s61
	s_cselect_b32 s62, s80, s60
	s_cselect_b32 s61, s25, s83
	s_cselect_b32 s60, s81, s82
	v_lshl_add_u64 v[164:165], s[58:59], 0, v[136:137]
	s_add_i32 m0, s57, 0xc000
	ds_read_b128 v[160:163], v168
	ds_read_b128 v[170:173], v168 offset:1024
	ds_read_b128 v[174:177], v168 offset:2048
	ds_read_b128 v[178:181], v168 offset:3072
	ds_read_b128 v[182:185], v168 offset:4096
	ds_read_b128 v[192:195], v168 offset:5120
	ds_read_b128 v[196:199], v168 offset:6144
	ds_read_b128 v[200:203], v168 offset:7168
	global_load_lds_dwordx4 v[164:165], off
	v_lshl_add_u64 v[164:165], s[58:59], 0, v[138:139]
	s_add_i32 m0, s57, 0xe000
	s_nop 0
	global_load_lds_dwordx4 v[164:165], off
	s_waitcnt lgkmcnt(8)
	s_barrier
	s_waitcnt lgkmcnt(0)
	s_setprio 1
	s_waitcnt lgkmcnt(0)
	v_mfma_f32_16x16x32_bf16 v[124:127], v[144:147], v[160:163], v[124:127]
	v_mfma_f32_16x16x32_bf16 v[120:123], v[152:155], v[160:163], v[120:123]
	v_mfma_f32_16x16x32_bf16 v[116:119], v[144:147], v[174:177], v[116:119]
	v_mfma_f32_16x16x32_bf16 v[112:115], v[152:155], v[174:177], v[112:115]
	v_mfma_f32_16x16x32_bf16 v[92:95], v[144:147], v[182:185], v[92:95]
	v_mfma_f32_16x16x32_bf16 v[88:91], v[152:155], v[182:185], v[88:91]
	v_mfma_f32_16x16x32_bf16 v[84:87], v[144:147], v[196:199], v[84:87]
	v_mfma_f32_16x16x32_bf16 v[76:79], v[152:155], v[196:199], v[76:79]
	v_mfma_f32_16x16x32_bf16 v[124:127], v[148:151], v[170:173], v[124:127]
	v_mfma_f32_16x16x32_bf16 v[120:123], v[156:159], v[170:173], v[120:123]
	v_mfma_f32_16x16x32_bf16 v[116:119], v[148:151], v[178:181], v[116:119]
	v_mfma_f32_16x16x32_bf16 v[112:115], v[156:159], v[178:181], v[112:115]
	v_mfma_f32_16x16x32_bf16 v[92:95], v[148:151], v[192:195], v[92:95]
	v_mfma_f32_16x16x32_bf16 v[88:91], v[156:159], v[192:195], v[88:91]
	v_mfma_f32_16x16x32_bf16 v[84:87], v[148:151], v[200:203], v[84:87]
	v_mfma_f32_16x16x32_bf16 v[76:79], v[156:159], v[200:203], v[76:79]
	s_setprio 0
	s_barrier
	s_add_i32 s85, s77, s64
	v_lshl_add_u64 v[164:165], s[60:61], 0, v[130:131]
	s_mov_b32 m0, s85
	ds_read_b128 v[204:207], v169
	ds_read_b128 v[208:211], v169 offset:1024
	ds_read_b128 v[212:215], v169 offset:2048
	ds_read_b128 v[216:219], v169 offset:3072
	global_load_lds_dwordx4 v[164:165], off
	v_lshl_add_u64 v[188:189], s[60:61], 0, v[134:135]
	s_add_i32 m0, s85, 0x2000
	s_nop 0
	global_load_lds_dwordx4 v[188:189], off
	s_barrier
	s_waitcnt lgkmcnt(0)
	s_setprio 1
	s_waitcnt lgkmcnt(0)
	v_mfma_f32_16x16x32_bf16 v[108:111], v[204:207], v[160:163], v[108:111]
	v_mfma_f32_16x16x32_bf16 v[104:107], v[212:215], v[160:163], v[104:107]
	v_mfma_f32_16x16x32_bf16 v[100:103], v[204:207], v[174:177], v[100:103]
	v_mfma_f32_16x16x32_bf16 v[96:99], v[212:215], v[174:177], v[96:99]
	v_mfma_f32_16x16x32_bf16 v[80:83], v[204:207], v[182:185], v[80:83]
	v_mfma_f32_16x16x32_bf16 v[72:75], v[212:215], v[182:185], v[72:75]
	v_mfma_f32_16x16x32_bf16 v[68:71], v[204:207], v[196:199], v[68:71]
	v_mfma_f32_16x16x32_bf16 v[64:67], v[212:215], v[196:199], v[64:67]
	v_mfma_f32_16x16x32_bf16 v[108:111], v[208:211], v[170:173], v[108:111]
	v_mfma_f32_16x16x32_bf16 v[104:107], v[216:219], v[170:173], v[104:107]
	v_mfma_f32_16x16x32_bf16 v[100:103], v[208:211], v[178:181], v[100:103]
	v_mfma_f32_16x16x32_bf16 v[96:99], v[216:219], v[178:181], v[96:99]
	v_mfma_f32_16x16x32_bf16 v[80:83], v[208:211], v[192:195], v[80:83]
	v_mfma_f32_16x16x32_bf16 v[72:75], v[216:219], v[192:195], v[72:75]
	v_mfma_f32_16x16x32_bf16 v[68:71], v[208:211], v[200:203], v[68:71]
	v_mfma_f32_16x16x32_bf16 v[64:67], v[216:219], v[200:203], v[64:67]
	s_setprio 0
	s_mov_b32 m0, s57
	v_lshl_add_u64 v[220:221], s[62:63], 0, v[128:129]
	s_barrier
	ds_read_b128 v[160:163], v168 offset:16384
	ds_read_b128 v[170:173], v168 offset:17408
	ds_read_b128 v[174:177], v168 offset:18432
	ds_read_b128 v[178:181], v168 offset:19456
	ds_read_b128 v[182:185], v168 offset:20480
	ds_read_b128 v[192:195], v168 offset:21504
	ds_read_b128 v[196:199], v168 offset:22528
	ds_read_b128 v[200:203], v168 offset:23552
	global_load_lds_dwordx4 v[220:221], off
	v_lshl_add_u64 v[222:223], s[62:63], 0, v[132:133]
	s_mov_b32 m0, s65
	s_nop 0
	global_load_lds_dwordx4 v[222:223], off
	s_barrier
	s_waitcnt lgkmcnt(0)
	s_setprio 1
	s_waitcnt lgkmcnt(0)
	v_mfma_f32_16x16x32_bf16 v[60:63], v[144:147], v[160:163], v[60:63]
	v_mfma_f32_16x16x32_bf16 v[56:59], v[152:155], v[160:163], v[56:59]
	v_mfma_f32_16x16x32_bf16 v[52:55], v[144:147], v[174:177], v[52:55]
	v_mfma_f32_16x16x32_bf16 v[44:47], v[152:155], v[174:177], v[44:47]
	v_mfma_f32_16x16x32_bf16 v[28:31], v[144:147], v[182:185], v[28:31]
	v_mfma_f32_16x16x32_bf16 v[24:27], v[152:155], v[182:185], v[24:27]
	v_mfma_f32_16x16x32_bf16 v[20:23], v[144:147], v[196:199], v[20:23]
	v_mfma_f32_16x16x32_bf16 v[16:19], v[152:155], v[196:199], v[16:19]
	v_mfma_f32_16x16x32_bf16 v[60:63], v[148:151], v[170:173], v[60:63]
	v_mfma_f32_16x16x32_bf16 v[56:59], v[156:159], v[170:173], v[56:59]
	v_mfma_f32_16x16x32_bf16 v[52:55], v[148:151], v[178:181], v[52:55]
	v_mfma_f32_16x16x32_bf16 v[44:47], v[156:159], v[178:181], v[44:47]
	v_mfma_f32_16x16x32_bf16 v[28:31], v[148:151], v[192:195], v[28:31]
	v_mfma_f32_16x16x32_bf16 v[24:27], v[156:159], v[192:195], v[24:27]
	v_mfma_f32_16x16x32_bf16 v[20:23], v[148:151], v[200:203], v[20:23]
	v_mfma_f32_16x16x32_bf16 v[16:19], v[156:159], v[200:203], v[16:19]
	s_setprio 0
	s_barrier
	s_add_u32 s86, s60, 0x80000
	s_addc_u32 s87, s61, 0
	s_add_i32 s85, s78, s64
	v_lshl_add_u64 v[144:145], s[86:87], 0, v[130:131]
	s_mov_b32 m0, s85
	s_nop 0
	global_load_lds_dwordx4 v[144:145], off
	v_lshl_add_u64 v[144:145], s[86:87], 0, v[134:135]
	s_add_i32 m0, s85, 0x2000
	s_nop 0
	global_load_lds_dwordx4 v[144:145], off
	s_waitcnt vmcnt(6)
	s_barrier
	s_setprio 1
	v_mfma_f32_16x16x32_bf16 v[48:51], v[204:207], v[160:163], v[48:51]
	v_mfma_f32_16x16x32_bf16 v[40:43], v[212:215], v[160:163], v[40:43]
	v_mfma_f32_16x16x32_bf16 v[36:39], v[204:207], v[174:177], v[36:39]
	v_mfma_f32_16x16x32_bf16 v[32:35], v[212:215], v[174:177], v[32:35]
	v_mfma_f32_16x16x32_bf16 v[12:15], v[204:207], v[182:185], v[12:15]
	v_mfma_f32_16x16x32_bf16 v[8:11], v[212:215], v[182:185], v[8:11]
	v_mfma_f32_16x16x32_bf16 v[4:7], v[204:207], v[196:199], v[4:7]
	v_mfma_f32_16x16x32_bf16 v[0:3], v[212:215], v[196:199], v[0:3]
	v_mfma_f32_16x16x32_bf16 v[48:51], v[208:211], v[170:173], v[48:51]
	v_mfma_f32_16x16x32_bf16 v[40:43], v[216:219], v[170:173], v[40:43]
	v_mfma_f32_16x16x32_bf16 v[36:39], v[208:211], v[178:181], v[36:39]
	v_mfma_f32_16x16x32_bf16 v[32:35], v[216:219], v[178:181], v[32:35]
	v_mfma_f32_16x16x32_bf16 v[12:15], v[208:211], v[192:195], v[12:15]
	v_mfma_f32_16x16x32_bf16 v[8:11], v[216:219], v[192:195], v[8:11]
	v_mfma_f32_16x16x32_bf16 v[4:7], v[208:211], v[200:203], v[4:7]
	v_mfma_f32_16x16x32_bf16 v[0:3], v[216:219], v[200:203], v[0:3]
	s_setprio 0
	s_add_i32 s85, 0, 0x18000
	v_add_u32_e32 v156, s85, v166
	s_barrier
	ds_read_b128 v[144:147], v156
	ds_read_b128 v[148:151], v156 offset:1024
	ds_read_b128 v[152:155], v156 offset:2048
	ds_read_b128 v[156:159], v156 offset:3072
	s_add_u32 s62, s62, 0x80000
	s_addc_u32 s63, s63, 0
	s_mov_b32 m0, s66
	v_lshl_add_u64 v[204:205], s[62:63], 0, v[128:129]
	ds_read_b128 v[160:163], v168 offset:32768
	ds_read_b128 v[170:173], v168 offset:33792
	ds_read_b128 v[174:177], v168 offset:34816
	ds_read_b128 v[178:181], v168 offset:35840
	ds_read_b128 v[182:185], v168 offset:36864
	ds_read_b128 v[192:195], v168 offset:37888
	ds_read_b128 v[196:199], v168 offset:38912
	ds_read_b128 v[200:203], v168 offset:39936
	global_load_lds_dwordx4 v[204:205], off
	v_lshl_add_u64 v[204:205], s[62:63], 0, v[132:133]
	s_mov_b32 m0, s67
	s_nop 0
	global_load_lds_dwordx4 v[204:205], off
	s_waitcnt lgkmcnt(8)
	s_barrier
	s_waitcnt lgkmcnt(0)
	s_setprio 1
	s_waitcnt lgkmcnt(0)
	v_mfma_f32_16x16x32_bf16 v[124:127], v[144:147], v[160:163], v[124:127]
	v_mfma_f32_16x16x32_bf16 v[120:123], v[152:155], v[160:163], v[120:123]
	v_mfma_f32_16x16x32_bf16 v[116:119], v[144:147], v[174:177], v[116:119]
	v_mfma_f32_16x16x32_bf16 v[112:115], v[152:155], v[174:177], v[112:115]
	v_mfma_f32_16x16x32_bf16 v[92:95], v[144:147], v[182:185], v[92:95]
	v_mfma_f32_16x16x32_bf16 v[88:91], v[152:155], v[182:185], v[88:91]
	v_mfma_f32_16x16x32_bf16 v[84:87], v[144:147], v[196:199], v[84:87]
	v_mfma_f32_16x16x32_bf16 v[76:79], v[152:155], v[196:199], v[76:79]
	v_mfma_f32_16x16x32_bf16 v[124:127], v[148:151], v[170:173], v[124:127]
	v_mfma_f32_16x16x32_bf16 v[120:123], v[156:159], v[170:173], v[120:123]
	v_mfma_f32_16x16x32_bf16 v[116:119], v[148:151], v[178:181], v[116:119]
	v_mfma_f32_16x16x32_bf16 v[112:115], v[156:159], v[178:181], v[112:115]
	v_mfma_f32_16x16x32_bf16 v[92:95], v[148:151], v[192:195], v[92:95]
	v_mfma_f32_16x16x32_bf16 v[88:91], v[156:159], v[192:195], v[88:91]
	v_mfma_f32_16x16x32_bf16 v[84:87], v[148:151], v[200:203], v[84:87]
	v_mfma_f32_16x16x32_bf16 v[76:79], v[156:159], v[200:203], v[76:79]
	s_setprio 0
	s_barrier
	s_add_i32 s62, 0, 0x1c000
	s_add_i32 s63, s85, s64
	v_add_u32_e32 v187, s62, v166
	v_lshl_add_u64 v[164:165], v[164:165], 0, s[6:7]
	s_mov_b32 m0, s63
	ds_read_b128 v[204:207], v187
	ds_read_b128 v[208:211], v187 offset:1024
	ds_read_b128 v[212:215], v187 offset:2048
	ds_read_b128 v[216:219], v187 offset:3072
	global_load_lds_dwordx4 v[164:165], off
	v_lshl_add_u64 v[164:165], v[188:189], 0, s[6:7]
	s_add_i32 m0, s63, 0x2000
	s_nop 0
	global_load_lds_dwordx4 v[164:165], off
	s_barrier
	s_waitcnt lgkmcnt(0)
	s_setprio 1
	s_waitcnt lgkmcnt(0)
	v_mfma_f32_16x16x32_bf16 v[108:111], v[204:207], v[160:163], v[108:111]
	v_mfma_f32_16x16x32_bf16 v[104:107], v[212:215], v[160:163], v[104:107]
	v_mfma_f32_16x16x32_bf16 v[100:103], v[204:207], v[174:177], v[100:103]
	v_mfma_f32_16x16x32_bf16 v[96:99], v[212:215], v[174:177], v[96:99]
	v_mfma_f32_16x16x32_bf16 v[80:83], v[204:207], v[182:185], v[80:83]
	v_mfma_f32_16x16x32_bf16 v[72:75], v[212:215], v[182:185], v[72:75]
	v_mfma_f32_16x16x32_bf16 v[68:71], v[204:207], v[196:199], v[68:71]
	v_mfma_f32_16x16x32_bf16 v[64:67], v[212:215], v[196:199], v[64:67]
	v_mfma_f32_16x16x32_bf16 v[108:111], v[208:211], v[170:173], v[108:111]
	v_mfma_f32_16x16x32_bf16 v[104:107], v[216:219], v[170:173], v[104:107]
	v_mfma_f32_16x16x32_bf16 v[100:103], v[208:211], v[178:181], v[100:103]
	v_mfma_f32_16x16x32_bf16 v[96:99], v[216:219], v[178:181], v[96:99]
	v_mfma_f32_16x16x32_bf16 v[80:83], v[208:211], v[192:195], v[80:83]
	v_mfma_f32_16x16x32_bf16 v[72:75], v[216:219], v[192:195], v[72:75]
	v_mfma_f32_16x16x32_bf16 v[68:71], v[208:211], v[200:203], v[68:71]
	v_mfma_f32_16x16x32_bf16 v[64:67], v[216:219], v[200:203], v[64:67]
	s_setprio 0
	s_mov_b32 m0, s73
	v_lshl_add_u64 v[164:165], v[220:221], 0, s[6:7]
	s_barrier
	ds_read_b128 v[160:163], v168 offset:49152
	ds_read_b128 v[170:173], v168 offset:50176
	ds_read_b128 v[174:177], v168 offset:51200
	ds_read_b128 v[178:181], v168 offset:52224
	ds_read_b128 v[182:185], v168 offset:53248
	ds_read_b128 v[192:195], v168 offset:54272
	ds_read_b128 v[196:199], v168 offset:55296
	ds_read_b128 v[200:203], v168 offset:56320
	global_load_lds_dwordx4 v[164:165], off
	v_lshl_add_u64 v[164:165], v[222:223], 0, s[6:7]
	s_mov_b32 m0, s74
	s_nop 0
	global_load_lds_dwordx4 v[164:165], off
	s_barrier
	s_waitcnt lgkmcnt(0)
	s_setprio 1
	s_waitcnt lgkmcnt(0)
	v_mfma_f32_16x16x32_bf16 v[60:63], v[144:147], v[160:163], v[60:63]
	v_mfma_f32_16x16x32_bf16 v[56:59], v[152:155], v[160:163], v[56:59]
	v_mfma_f32_16x16x32_bf16 v[52:55], v[144:147], v[174:177], v[52:55]
	v_mfma_f32_16x16x32_bf16 v[44:47], v[152:155], v[174:177], v[44:47]
	v_mfma_f32_16x16x32_bf16 v[28:31], v[144:147], v[182:185], v[28:31]
	v_mfma_f32_16x16x32_bf16 v[24:27], v[152:155], v[182:185], v[24:27]
	v_mfma_f32_16x16x32_bf16 v[20:23], v[144:147], v[196:199], v[20:23]
	v_mfma_f32_16x16x32_bf16 v[16:19], v[152:155], v[196:199], v[16:19]
	v_mfma_f32_16x16x32_bf16 v[60:63], v[148:151], v[170:173], v[60:63]
	v_mfma_f32_16x16x32_bf16 v[56:59], v[156:159], v[170:173], v[56:59]
	v_mfma_f32_16x16x32_bf16 v[52:55], v[148:151], v[178:181], v[52:55]
	v_mfma_f32_16x16x32_bf16 v[44:47], v[156:159], v[178:181], v[44:47]
	v_mfma_f32_16x16x32_bf16 v[28:31], v[148:151], v[192:195], v[28:31]
	v_mfma_f32_16x16x32_bf16 v[24:27], v[156:159], v[192:195], v[24:27]
	v_mfma_f32_16x16x32_bf16 v[20:23], v[148:151], v[200:203], v[20:23]
	v_mfma_f32_16x16x32_bf16 v[16:19], v[156:159], v[200:203], v[16:19]
	s_setprio 0
	s_barrier
	s_add_u32 s60, s60, 0x80080
	s_addc_u32 s61, s61, 0
	s_add_i32 s62, s62, s64
	v_lshl_add_u64 v[144:145], s[60:61], 0, v[130:131]
	s_mov_b32 m0, s62
	s_nop 0
	global_load_lds_dwordx4 v[144:145], off
	v_lshl_add_u64 v[144:145], s[60:61], 0, v[134:135]
	s_add_i32 m0, s62, 0x2000
	s_nop 0
	global_load_lds_dwordx4 v[144:145], off
	s_waitcnt vmcnt(6)
	s_barrier
	s_setprio 1
	v_mfma_f32_16x16x32_bf16 v[48:51], v[204:207], v[160:163], v[48:51]
	v_mfma_f32_16x16x32_bf16 v[40:43], v[212:215], v[160:163], v[40:43]
	v_mfma_f32_16x16x32_bf16 v[36:39], v[204:207], v[174:177], v[36:39]
	v_mfma_f32_16x16x32_bf16 v[32:35], v[212:215], v[174:177], v[32:35]
	v_mfma_f32_16x16x32_bf16 v[12:15], v[204:207], v[182:185], v[12:15]
	v_mfma_f32_16x16x32_bf16 v[8:11], v[212:215], v[182:185], v[8:11]
	v_mfma_f32_16x16x32_bf16 v[4:7], v[204:207], v[196:199], v[4:7]
	v_mfma_f32_16x16x32_bf16 v[0:3], v[212:215], v[196:199], v[0:3]
	v_mfma_f32_16x16x32_bf16 v[48:51], v[208:211], v[170:173], v[48:51]
	v_mfma_f32_16x16x32_bf16 v[40:43], v[216:219], v[170:173], v[40:43]
	v_mfma_f32_16x16x32_bf16 v[36:39], v[208:211], v[178:181], v[36:39]
	v_mfma_f32_16x16x32_bf16 v[32:35], v[216:219], v[178:181], v[32:35]
	v_mfma_f32_16x16x32_bf16 v[12:15], v[208:211], v[192:195], v[12:15]
	v_mfma_f32_16x16x32_bf16 v[8:11], v[216:219], v[192:195], v[8:11]
	v_mfma_f32_16x16x32_bf16 v[4:7], v[208:211], v[200:203], v[4:7]
	v_mfma_f32_16x16x32_bf16 v[0:3], v[216:219], v[200:203], v[0:3]
	s_setprio 0
	s_add_i32 s84, s84, 2
	s_add_u32 s58, s58, 0x100
	s_addc_u32 s59, s59, 0
	s_add_u32 s82, s82, 0x100
	s_addc_u32 s83, s83, 0
	s_cmp_gt_u32 s84, 29
	s_barrier
	s_cbranch_scc0 .LBB0_476
	v_mov_b32_e32 v146, v254
	s_lshl_b32 s51, s56, 8
	v_readfirstlane_b32 s25, v146
	s_ashr_i32 s56, s25, 2
	s_andn2_b32 s56, s56, 63
	s_lshr_b32 s25, s25, 1
	s_add_i32 s56, s56, s51
	s_lshl_b32 s51, s79, 8
	s_and_b32 s25, s25, 0x60
	s_or_b32 s25, s25, s51
	v_lshrrev_b32_e32 v144, 1, v146
	v_and_or_b32 v144, v144, 24, s25
	s_ashr_i32 s25, s56, 12
	s_mul_i32 s58, s25, 0xc00
	v_and_or_b32 v162, v146, 15, s56
	v_or_b32_e32 v170, 16, v162
	s_ashr_i32 s59, s58, 31
	v_ashrrev_i32_e32 v163, 31, v162
	v_ashrrev_i32_e32 v171, 31, v170
	s_lshl_b64 s[58:59], s[58:59], 2
	v_ashrrev_i32_e32 v145, 31, v144
	v_lshlrev_b64 v[164:165], 12, v[162:163]
	v_lshlrev_b64 v[188:189], 12, v[170:171]
	s_add_u32 s58, s71, s58
	v_lshlrev_b64 v[144:145], 2, v[144:145]
	v_lshl_add_u64 v[146:147], s[36:37], 0, v[164:165]
	v_lshl_add_u64 v[170:171], s[36:37], 0, v[188:189]
	s_addc_u32 s59, s72, s59
	v_lshl_add_u64 v[158:159], v[146:147], 0, v[144:145]
	v_lshl_add_u64 v[182:183], v[170:171], 0, v[144:145]
	v_lshl_add_u64 v[204:205], s[58:59], 0, v[144:145]
	global_load_dwordx4 v[146:149], v[158:159], off offset:16
	global_load_dwordx4 v[150:153], v[158:159], off
	global_load_dwordx4 v[154:157], v[158:159], off offset:528
	s_nop 0
	global_load_dwordx4 v[158:161], v[158:159], off offset:512
	s_nop 0
	global_load_dwordx4 v[170:173], v[182:183], off offset:16
	global_load_dwordx4 v[174:177], v[182:183], off
	global_load_dwordx4 v[178:181], v[182:183], off offset:528
	s_nop 0
	global_load_dwordx4 v[182:185], v[182:183], off offset:512
	s_nop 0
	global_load_dwordx4 v[192:195], v[204:205], off
	global_load_dwordx4 v[196:199], v[204:205], off offset:16
	global_load_dwordx4 v[200:203], v[204:205], off offset:512
	s_nop 0
	global_load_dwordx4 v[204:207], v[204:205], off offset:528
	v_or_b32_e32 v208, 32, v162
	v_ashrrev_i32_e32 v209, 31, v208
	v_lshl_add_u64 v[212:213], s[26:27], 0, v[164:165]
	v_lshlrev_b64 v[208:209], 12, v[208:209]
	v_lshl_add_u64 v[212:213], v[212:213], 0, v[144:145]
	v_lshl_add_u64 v[214:215], s[36:37], 0, v[208:209]
	v_lshl_add_u64 v[214:215], v[214:215], 0, v[144:145]
	v_or_b32_e32 v210, 48, v162
	v_ashrrev_i32_e32 v211, 31, v210
	v_lshlrev_b64 v[210:211], 12, v[210:211]
	v_lshl_add_u64 v[188:189], s[26:27], 0, v[188:189]
	v_lshl_add_u64 v[216:217], s[36:37], 0, v[210:211]
	v_lshl_add_u64 v[188:189], v[188:189], 0, v[144:145]
	v_lshl_add_u64 v[216:217], v[216:217], 0, v[144:145]
	v_lshl_add_u64 v[164:165], v[164:165], 0, s[0:1]
	s_mov_b32 s79, s24
	s_mov_b32 s56, s50
	s_and_b64 vcc, exec, s[4:5]
	s_mov_b64 s[60:61], s[54:55]
	s_mov_b64 s[58:59], s[52:53]
	s_waitcnt vmcnt(0)
	v_pk_mul_f32 v[222:223], v[148:149], s[12:13] op_sel_hi:[1,0]
	v_pk_mul_f32 v[218:219], v[152:153], s[12:13] op_sel_hi:[1,0]
	v_pk_mul_f32 v[220:221], v[150:151], s[12:13] op_sel_hi:[1,0]
	v_pk_mul_f32 v[224:225], v[146:147], s[12:13] op_sel_hi:[1,0]
	v_pk_add_f32 v[146:147], v[194:195], 1.0 op_sel_hi:[1,0]
	v_pk_add_f32 v[148:149], v[192:193], 1.0 op_sel_hi:[1,0]
	v_pk_mul_f32 v[226:227], v[160:161], s[12:13] op_sel_hi:[1,0]
	v_pk_mul_f32 v[228:229], v[158:159], s[12:13] op_sel_hi:[1,0]
	v_pk_mul_f32 v[230:231], v[156:157], s[12:13] op_sel_hi:[1,0]
	v_pk_mul_f32 v[232:233], v[154:155], s[12:13] op_sel_hi:[1,0]
	v_pk_add_f32 v[150:151], v[198:199], 1.0 op_sel_hi:[1,0]
	v_pk_add_f32 v[152:153], v[196:197], 1.0 op_sel_hi:[1,0]
	v_pk_add_f32 v[154:155], v[202:203], 1.0 op_sel_hi:[1,0]
	v_pk_add_f32 v[156:157], v[200:201], 1.0 op_sel_hi:[1,0]
	v_pk_add_f32 v[158:159], v[206:207], 1.0 op_sel_hi:[1,0]
	v_pk_add_f32 v[160:161], v[204:205], 1.0 op_sel_hi:[1,0]
	v_pk_fma_f32 v[126:127], v[126:127], v[146:147], v[218:219]
	v_pk_fma_f32 v[124:125], v[124:125], v[148:149], v[220:221]
	v_pk_fma_f32 v[122:123], v[122:123], v[150:151], v[222:223]
	v_pk_fma_f32 v[120:121], v[120:121], v[152:153], v[224:225]
	v_pk_fma_f32 v[110:111], v[110:111], v[154:155], v[226:227]
	v_pk_fma_f32 v[108:109], v[108:109], v[156:157], v[228:229]
	v_pk_fma_f32 v[106:107], v[106:107], v[158:159], v[230:231]
	v_pk_fma_f32 v[104:105], v[104:105], v[160:161], v[232:233]
	global_store_dwordx4 v[212:213], v[124:127], off
	global_store_dwordx4 v[212:213], v[120:123], off offset:16
	global_store_dwordx4 v[212:213], v[108:111], off offset:512
	global_store_dwordx4 v[212:213], v[104:107], off offset:528
	global_load_dwordx4 v[104:107], v[214:215], off offset:16
	s_nop 0
	global_load_dwordx4 v[108:111], v[214:215], off
	global_load_dwordx4 v[120:123], v[214:215], off offset:528
	global_load_dwordx4 v[124:127], v[214:215], off offset:512
	v_pk_mul_f32 v[176:177], v[176:177], s[12:13] op_sel_hi:[1,0]
	v_pk_mul_f32 v[174:175], v[174:175], s[12:13] op_sel_hi:[1,0]
	v_pk_mul_f32 v[172:173], v[172:173], s[12:13] op_sel_hi:[1,0]
	v_pk_mul_f32 v[170:171], v[170:171], s[12:13] op_sel_hi:[1,0]
	v_pk_mul_f32 v[184:185], v[184:185], s[12:13] op_sel_hi:[1,0]
	v_pk_mul_f32 v[182:183], v[182:183], s[12:13] op_sel_hi:[1,0]
	v_pk_mul_f32 v[180:181], v[180:181], s[12:13] op_sel_hi:[1,0]
	v_pk_mul_f32 v[178:179], v[178:179], s[12:13] op_sel_hi:[1,0]
	v_pk_fma_f32 v[118:119], v[118:119], v[146:147], v[176:177]
	v_pk_fma_f32 v[116:117], v[116:117], v[148:149], v[174:175]
	v_pk_fma_f32 v[114:115], v[114:115], v[150:151], v[172:173]
	v_pk_fma_f32 v[112:113], v[112:113], v[152:153], v[170:171]
	v_pk_fma_f32 v[102:103], v[102:103], v[154:155], v[184:185]
	v_pk_fma_f32 v[100:101], v[100:101], v[156:157], v[182:183]
	v_pk_fma_f32 v[98:99], v[98:99], v[158:159], v[180:181]
	v_pk_fma_f32 v[96:97], v[96:97], v[160:161], v[178:179]
	global_store_dwordx4 v[188:189], v[116:119], off
	global_store_dwordx4 v[188:189], v[112:115], off offset:16
	global_store_dwordx4 v[188:189], v[100:103], off offset:512
	global_store_dwordx4 v[188:189], v[96:99], off offset:528
	global_load_dwordx4 v[96:99], v[216:217], off
	s_nop 0
	global_load_dwordx4 v[100:103], v[216:217], off offset:16
	global_load_dwordx4 v[112:115], v[216:217], off offset:512
	global_load_dwordx4 v[116:119], v[216:217], off offset:528
	v_lshl_add_u64 v[172:173], s[26:27], 0, v[208:209]
	v_lshl_add_u64 v[174:175], s[36:37], 0, v[164:165]
	v_lshl_add_u64 v[172:173], v[172:173], 0, v[144:145]
	v_lshl_add_u64 v[174:175], v[174:175], 0, v[144:145]
	v_add_u32_e32 v170, 0x90, v162
	v_ashrrev_i32_e32 v171, 31, v170
	v_lshlrev_b64 v[170:171], 12, v[170:171]
	v_lshl_add_u64 v[176:177], s[26:27], 0, v[210:211]
	v_lshl_add_u64 v[178:179], s[36:37], 0, v[170:171]
	v_lshl_add_u64 v[176:177], v[176:177], 0, v[144:145]
	v_lshl_add_u64 v[178:179], v[178:179], 0, v[144:145]
	s_waitcnt vmcnt(8)
	v_pk_mul_f32 v[106:107], v[106:107], s[12:13] op_sel_hi:[1,0]
	v_pk_mul_f32 v[110:111], v[110:111], s[12:13] op_sel_hi:[1,0]
	v_pk_mul_f32 v[108:109], v[108:109], s[12:13] op_sel_hi:[1,0]
	v_pk_mul_f32 v[104:105], v[104:105], s[12:13] op_sel_hi:[1,0]
	v_pk_mul_f32 v[126:127], v[126:127], s[12:13] op_sel_hi:[1,0]
	v_pk_mul_f32 v[124:125], v[124:125], s[12:13] op_sel_hi:[1,0]
	v_pk_mul_f32 v[122:123], v[122:123], s[12:13] op_sel_hi:[1,0]
	v_pk_mul_f32 v[120:121], v[120:121], s[12:13] op_sel_hi:[1,0]
	v_pk_fma_f32 v[94:95], v[94:95], v[146:147], v[110:111]
	v_pk_fma_f32 v[92:93], v[92:93], v[148:149], v[108:109]
	v_pk_fma_f32 v[90:91], v[90:91], v[150:151], v[106:107]
	v_pk_fma_f32 v[88:89], v[88:89], v[152:153], v[104:105]
	v_pk_fma_f32 v[82:83], v[82:83], v[154:155], v[126:127]
	v_pk_fma_f32 v[80:81], v[80:81], v[156:157], v[124:125]
	v_pk_fma_f32 v[74:75], v[74:75], v[158:159], v[122:123]
	v_pk_fma_f32 v[72:73], v[72:73], v[160:161], v[120:121]
	global_store_dwordx4 v[172:173], v[92:95], off
	global_store_dwordx4 v[172:173], v[88:91], off offset:16
	global_store_dwordx4 v[172:173], v[80:83], off offset:512
	global_store_dwordx4 v[172:173], v[72:75], off offset:528
	global_load_dwordx4 v[72:75], v[174:175], off offset:16
	s_nop 0
	global_load_dwordx4 v[80:83], v[174:175], off
	global_load_dwordx4 v[88:91], v[174:175], off offset:528
	global_load_dwordx4 v[92:95], v[174:175], off offset:512
	s_waitcnt vmcnt(8)
	v_pk_mul_f32 v[98:99], v[98:99], s[12:13] op_sel_hi:[1,0]
	v_pk_mul_f32 v[96:97], v[96:97], s[12:13] op_sel_hi:[1,0]
	v_pk_mul_f32 v[102:103], v[102:103], s[12:13] op_sel_hi:[1,0]
	v_pk_mul_f32 v[100:101], v[100:101], s[12:13] op_sel_hi:[1,0]
	v_pk_mul_f32 v[104:105], v[114:115], s[12:13] op_sel_hi:[1,0]
	v_pk_mul_f32 v[106:107], v[112:113], s[12:13] op_sel_hi:[1,0]
	v_pk_mul_f32 v[108:109], v[118:119], s[12:13] op_sel_hi:[1,0]
	v_pk_mul_f32 v[110:111], v[116:117], s[12:13] op_sel_hi:[1,0]
	v_pk_fma_f32 v[86:87], v[86:87], v[146:147], v[98:99]
	v_pk_fma_f32 v[84:85], v[84:85], v[148:149], v[96:97]
	v_pk_fma_f32 v[78:79], v[78:79], v[150:151], v[102:103]
	v_pk_fma_f32 v[76:77], v[76:77], v[152:153], v[100:101]
	v_pk_fma_f32 v[70:71], v[70:71], v[154:155], v[104:105]
	v_pk_fma_f32 v[68:69], v[68:69], v[156:157], v[106:107]
	v_pk_fma_f32 v[66:67], v[66:67], v[158:159], v[108:109]
	v_pk_fma_f32 v[64:65], v[64:65], v[160:161], v[110:111]
	global_store_dwordx4 v[176:177], v[84:87], off
	global_store_dwordx4 v[176:177], v[76:79], off offset:16
	global_store_dwordx4 v[176:177], v[68:71], off offset:512
	global_store_dwordx4 v[176:177], v[64:67], off offset:528
	global_load_dwordx4 v[64:67], v[178:179], off
	s_nop 0
	global_load_dwordx4 v[68:71], v[178:179], off offset:16
	global_load_dwordx4 v[76:79], v[178:179], off offset:512
	global_load_dwordx4 v[84:87], v[178:179], off offset:528
	v_add_u32_e32 v96, 0xa0, v162
	v_ashrrev_i32_e32 v97, 31, v96
	v_lshlrev_b64 v[96:97], 12, v[96:97]
	v_lshl_add_u64 v[100:101], s[26:27], 0, v[164:165]
	v_lshl_add_u64 v[102:103], s[36:37], 0, v[96:97]
	v_lshl_add_u64 v[100:101], v[100:101], 0, v[144:145]
	v_lshl_add_u64 v[102:103], v[102:103], 0, v[144:145]
	v_add_u32_e32 v98, 0xb0, v162
	v_ashrrev_i32_e32 v99, 31, v98
	v_lshlrev_b64 v[98:99], 12, v[98:99]
	v_lshl_add_u64 v[104:105], s[26:27], 0, v[170:171]
	v_lshl_add_u64 v[106:107], s[36:37], 0, v[98:99]
	v_lshl_add_u64 v[104:105], v[104:105], 0, v[144:145]
	v_lshl_add_u64 v[106:107], v[106:107], 0, v[144:145]
	s_waitcnt vmcnt(8)
	v_pk_mul_f32 v[74:75], v[74:75], s[12:13] op_sel_hi:[1,0]
	v_pk_mul_f32 v[82:83], v[82:83], s[12:13] op_sel_hi:[1,0]
	v_pk_mul_f32 v[80:81], v[80:81], s[12:13] op_sel_hi:[1,0]
	v_pk_mul_f32 v[72:73], v[72:73], s[12:13] op_sel_hi:[1,0]
	v_pk_mul_f32 v[94:95], v[94:95], s[12:13] op_sel_hi:[1,0]
	v_pk_mul_f32 v[92:93], v[92:93], s[12:13] op_sel_hi:[1,0]
	v_pk_mul_f32 v[90:91], v[90:91], s[12:13] op_sel_hi:[1,0]
	v_pk_mul_f32 v[88:89], v[88:89], s[12:13] op_sel_hi:[1,0]
	v_pk_fma_f32 v[62:63], v[62:63], v[146:147], v[82:83]
	v_pk_fma_f32 v[60:61], v[60:61], v[148:149], v[80:81]
	v_pk_fma_f32 v[58:59], v[58:59], v[150:151], v[74:75]
	v_pk_fma_f32 v[56:57], v[56:57], v[152:153], v[72:73]
	v_pk_fma_f32 v[50:51], v[50:51], v[154:155], v[94:95]
	v_pk_fma_f32 v[48:49], v[48:49], v[156:157], v[92:93]
	v_pk_fma_f32 v[42:43], v[42:43], v[158:159], v[90:91]
	v_pk_fma_f32 v[40:41], v[40:41], v[160:161], v[88:89]
	global_store_dwordx4 v[100:101], v[60:63], off
	global_store_dwordx4 v[100:101], v[56:59], off offset:16
	global_store_dwordx4 v[100:101], v[48:51], off offset:512
	global_store_dwordx4 v[100:101], v[40:43], off offset:528
	global_load_dwordx4 v[40:43], v[102:103], off offset:16
	s_nop 0
	global_load_dwordx4 v[48:51], v[102:103], off
	global_load_dwordx4 v[56:59], v[102:103], off offset:528
	global_load_dwordx4 v[60:63], v[102:103], off offset:512
	s_waitcnt vmcnt(8)
	v_pk_mul_f32 v[66:67], v[66:67], s[12:13] op_sel_hi:[1,0]
	v_pk_mul_f32 v[64:65], v[64:65], s[12:13] op_sel_hi:[1,0]
	v_pk_mul_f32 v[70:71], v[70:71], s[12:13] op_sel_hi:[1,0]
	v_pk_mul_f32 v[68:69], v[68:69], s[12:13] op_sel_hi:[1,0]
	v_pk_mul_f32 v[72:73], v[78:79], s[12:13] op_sel_hi:[1,0]
	v_pk_mul_f32 v[74:75], v[76:77], s[12:13] op_sel_hi:[1,0]
	v_pk_mul_f32 v[76:77], v[86:87], s[12:13] op_sel_hi:[1,0]
	v_pk_mul_f32 v[78:79], v[84:85], s[12:13] op_sel_hi:[1,0]
	v_pk_fma_f32 v[54:55], v[54:55], v[146:147], v[66:67]
	v_pk_fma_f32 v[52:53], v[52:53], v[148:149], v[64:65]
	v_pk_fma_f32 v[46:47], v[46:47], v[150:151], v[70:71]
	v_pk_fma_f32 v[44:45], v[44:45], v[152:153], v[68:69]
	v_pk_fma_f32 v[38:39], v[38:39], v[154:155], v[72:73]
	v_pk_fma_f32 v[36:37], v[36:37], v[156:157], v[74:75]
	v_pk_fma_f32 v[34:35], v[34:35], v[158:159], v[76:77]
	v_pk_fma_f32 v[32:33], v[32:33], v[160:161], v[78:79]
	global_store_dwordx4 v[104:105], v[52:55], off
	global_store_dwordx4 v[104:105], v[44:47], off offset:16
	global_store_dwordx4 v[104:105], v[36:39], off offset:512
	global_store_dwordx4 v[104:105], v[32:35], off offset:528
	global_load_dwordx4 v[32:35], v[106:107], off
	s_nop 0
	global_load_dwordx4 v[36:39], v[106:107], off offset:16
	global_load_dwordx4 v[44:47], v[106:107], off offset:512
	global_load_dwordx4 v[52:55], v[106:107], off offset:528
	v_lshl_add_u64 v[64:65], s[26:27], 0, v[96:97]
	v_lshl_add_u64 v[64:65], v[64:65], 0, v[144:145]
	v_lshl_add_u64 v[66:67], s[26:27], 0, v[98:99]
	v_lshl_add_u64 v[66:67], v[66:67], 0, v[144:145]
	s_waitcnt vmcnt(8)
	v_pk_mul_f32 v[42:43], v[42:43], s[12:13] op_sel_hi:[1,0]
	v_pk_mul_f32 v[50:51], v[50:51], s[12:13] op_sel_hi:[1,0]
	v_pk_mul_f32 v[48:49], v[48:49], s[12:13] op_sel_hi:[1,0]
	v_pk_mul_f32 v[40:41], v[40:41], s[12:13] op_sel_hi:[1,0]
	v_pk_mul_f32 v[62:63], v[62:63], s[12:13] op_sel_hi:[1,0]
	v_pk_mul_f32 v[60:61], v[60:61], s[12:13] op_sel_hi:[1,0]
	v_pk_mul_f32 v[58:59], v[58:59], s[12:13] op_sel_hi:[1,0]
	v_pk_mul_f32 v[56:57], v[56:57], s[12:13] op_sel_hi:[1,0]
	v_pk_fma_f32 v[30:31], v[30:31], v[146:147], v[50:51]
	v_pk_fma_f32 v[28:29], v[28:29], v[148:149], v[48:49]
	v_pk_fma_f32 v[26:27], v[26:27], v[150:151], v[42:43]
	v_pk_fma_f32 v[24:25], v[24:25], v[152:153], v[40:41]
	v_pk_fma_f32 v[14:15], v[14:15], v[154:155], v[62:63]
	v_pk_fma_f32 v[12:13], v[12:13], v[156:157], v[60:61]
	v_pk_fma_f32 v[10:11], v[10:11], v[158:159], v[58:59]
	v_pk_fma_f32 v[8:9], v[8:9], v[160:161], v[56:57]
	global_store_dwordx4 v[64:65], v[28:31], off
	global_store_dwordx4 v[64:65], v[24:27], off offset:16
	global_store_dwordx4 v[64:65], v[12:15], off offset:512
	global_store_dwordx4 v[64:65], v[8:11], off offset:528
	s_waitcnt vmcnt(4)
	v_pk_mul_f32 v[34:35], v[34:35], s[12:13] op_sel_hi:[1,0]
	v_pk_mul_f32 v[32:33], v[32:33], s[12:13] op_sel_hi:[1,0]
	v_pk_mul_f32 v[38:39], v[38:39], s[12:13] op_sel_hi:[1,0]
	v_pk_mul_f32 v[36:37], v[36:37], s[12:13] op_sel_hi:[1,0]
	v_pk_mul_f32 v[40:41], v[46:47], s[12:13] op_sel_hi:[1,0]
	v_pk_mul_f32 v[42:43], v[44:45], s[12:13] op_sel_hi:[1,0]
	v_pk_mul_f32 v[44:45], v[54:55], s[12:13] op_sel_hi:[1,0]
	v_pk_mul_f32 v[46:47], v[52:53], s[12:13] op_sel_hi:[1,0]
	v_pk_fma_f32 v[10:11], v[22:23], v[146:147], v[34:35]
	v_pk_fma_f32 v[8:9], v[20:21], v[148:149], v[32:33]
	v_pk_fma_f32 v[14:15], v[18:19], v[150:151], v[38:39]
	v_pk_fma_f32 v[12:13], v[16:17], v[152:153], v[36:37]
	v_pk_fma_f32 v[6:7], v[6:7], v[154:155], v[40:41]
	v_pk_fma_f32 v[4:5], v[4:5], v[156:157], v[42:43]
	v_pk_fma_f32 v[2:3], v[2:3], v[158:159], v[44:45]
	v_pk_fma_f32 v[0:1], v[0:1], v[160:161], v[46:47]
	global_store_dwordx4 v[66:67], v[8:11], off
	global_store_dwordx4 v[66:67], v[12:15], off offset:16
	global_store_dwordx4 v[66:67], v[4:7], off offset:512
	global_store_dwordx4 v[66:67], v[0:3], off offset:528
	s_cbranch_vccz .LBB0_469
	s_waitcnt vmcnt(0)
	s_cmpk_gt_u32 s3, 0xff
	s_cbranch_scc1 .LBB0_480
	s_barrier
